# attention K/V staging deepened to three LDS stages (tile j+2 staged while tile j is computed, counted vmcnt at the tile barrier); next-tile staging issued from inside the tile body
# speedup vs baseline: 1.0029x; 1.0029x over previous
; #define SBAR() __builtin_amdgcn_sched_barrier(0)
; __device__ __forceinline__ void attn_unit(const bf16_t* __restrict__ Qb, const bf16_t* __restrict__ Kh, const bf16_t* __restrict__ Vh, bf16_t* __restrict__ Ob,
;                                           LAS unsigned char* lds, float MB, int tid, int nrows, int t0, int t1, float* part, float* partl) {
;     ...
;     f32x16 p0, p1; bf16x8 pa0, pa1, pa2, pa3;
;     SDMA(t0 * KVBLK, 0); asm volatile("s_waitcnt vmcnt(0)" ::: "memory"); __syncthreads();
;     for (int j = t0; j < t1; ++j) {
;         const int b = (j - t0) & 1; const bool more = (j + 1 < t1);
;         if (more) { if (b) SDMA((j + 1) * KVBLK, 0); else SDMA((j + 1) * KVBLK, 1); }
;         if (act) {
;         SBAR(); qkt(p0, p1, K_lds + b * SHM_K, qr, qt, r32, hi);
;         expP(p0, p1, MB);
;         if (j == NT - 1) maskLast(p0, p1);
;         finishP(p0, p1, l_reg, pa0, pa1, pa2, pa3); SBAR();
;         pv_d0(o, vb0 + b * SHM_V, pa0, pa1, pa2, pa3);
;         }
;         asm volatile("s_waitcnt vmcnt(0)" ::: "memory");
;         __syncthreads();
.LBB0_136:
	s_mov_b32 s65, 0
	v_mov_b32_e32 v155, 0
	v_mov_b32_e32 v149, 0
	s_add_i32 s61, s58, 0x4000
	s_add_i32 s62, s58, 0x10000
	s_add_i32 s63, s58, 0x12000
	s_add_i32 s52, s52, 64
	s_mov_b32 s64, 0
	v_mov_b32_e32 v48, 0
	v_mov_b32_e32 v49, v155
	v_mov_b32_e32 v50, v155
	v_mov_b32_e32 v51, v155
	v_mov_b32_e32 v52, v155
	v_mov_b32_e32 v53, v155
	v_mov_b32_e32 v54, v155
	v_mov_b32_e32 v55, v155
	v_mov_b32_e32 v56, v155
	v_mov_b32_e32 v57, v155
	v_mov_b32_e32 v58, v155
	v_mov_b32_e32 v59, v155
	v_mov_b32_e32 v60, v155
	v_mov_b32_e32 v61, v155
	v_mov_b32_e32 v62, v155
	v_mov_b32_e32 v63, v155
	v_mov_b32_e32 v32, 0
	v_mov_b32_e32 v33, v155
	v_mov_b32_e32 v34, v155
	v_mov_b32_e32 v35, v155
	v_mov_b32_e32 v36, v155
	v_mov_b32_e32 v37, v155
	v_mov_b32_e32 v38, v155
	v_mov_b32_e32 v39, v155
	v_mov_b32_e32 v40, v155
	v_mov_b32_e32 v41, v155
	v_mov_b32_e32 v42, v155
	v_mov_b32_e32 v43, v155
	v_mov_b32_e32 v44, v155
	v_mov_b32_e32 v45, v155
	v_mov_b32_e32 v46, v155
	v_mov_b32_e32 v47, v155
	v_mov_b32_e32 v16, 0
	v_mov_b32_e32 v17, v155
	v_mov_b32_e32 v18, v155
	v_mov_b32_e32 v19, v155
	v_mov_b32_e32 v20, v155
	v_mov_b32_e32 v21, v155
	v_mov_b32_e32 v22, v155
	v_mov_b32_e32 v23, v155
	v_mov_b32_e32 v24, v155
	v_mov_b32_e32 v25, v155
	v_mov_b32_e32 v26, v155
	v_mov_b32_e32 v27, v155
	v_mov_b32_e32 v28, v155
	v_mov_b32_e32 v29, v155
	v_mov_b32_e32 v30, v155
	v_mov_b32_e32 v31, v155
	v_mov_b32_e32 v0, 0
	v_mov_b32_e32 v1, v155
	v_mov_b32_e32 v2, v155
	v_mov_b32_e32 v3, v155
	v_mov_b32_e32 v4, v155
	v_mov_b32_e32 v5, v155
	v_mov_b32_e32 v6, v155
	v_mov_b32_e32 v7, v155
	v_mov_b32_e32 v8, v155
	v_mov_b32_e32 v9, v155
	v_mov_b32_e32 v10, v155
	v_mov_b32_e32 v11, v155
	v_mov_b32_e32 v12, v155
	v_mov_b32_e32 v13, v155
	v_mov_b32_e32 v14, v155
	v_mov_b32_e32 v15, v155
	s_branch .LBB0_138
.LBB0_137:
	s_cmp_eq_u32 s71, 0
	s_cbranch_scc1 .Latt_w0
	s_waitcnt vmcnt(5)
	s_branch .Latt_w1

; #define SBAR() __builtin_amdgcn_sched_barrier(0)
; __device__ __forceinline__ void attn_unit(const bf16_t* __restrict__ Qb, const bf16_t* __restrict__ Kh, const bf16_t* __restrict__ Vh, bf16_t* __restrict__ Ob,
;                                           LAS unsigned char* lds, float MB, int tid, int nrows, int t0, int t1, float* part, float* partl) {
;     ...
;     f32x16 p0, p1; bf16x8 pa0, pa1, pa2, pa3;
;     SDMA(t0 * KVBLK, 0); asm volatile("s_waitcnt vmcnt(0)" ::: "memory"); __syncthreads();
;     for (int j = t0; j < t1; ++j) {
;         const int b = (j - t0) & 1; const bool more = (j + 1 < t1);
;         if (more) { if (b) SDMA((j + 1) * KVBLK, 0); else SDMA((j + 1) * KVBLK, 1); }
;         if (act) {
;         SBAR(); qkt(p0, p1, K_lds + b * SHM_K, qr, qt, r32, hi);
;         expP(p0, p1, MB);
;         if (j == NT - 1) maskLast(p0, p1);
;         finishP(p0, p1, l_reg, pa0, pa1, pa2, pa3); SBAR();
;         pv_d0(o, vb0 + b * SHM_V, pa0, pa1, pa2, pa3);
.Latt_w1:
	s_add_i32 s65, s65, 1
	s_cmp_eq_u32 s65, 3
	s_cselect_b32 s65, 0, s65
	s_add_i32 s64, s64, 1
	s_add_i32 s52, s52, 64
	s_add_i32 s42, s46, s64
	s_cmp_ge_i32 s42, s47
	s_waitcnt lgkmcnt(0)
	s_barrier
	s_cbranch_scc1 .LBB0_142
.LBB0_138:
	s_add_i32 s66, s46, s64
	s_cmp_lg_u32 s64, 0
	s_cbranch_scc1 .Latt_st2
	s_add_i32 s42, s66, 1
	s_cmp_ge_i32 s42, s47
	s_cbranch_scc1 .Latt_st2
	s_add_i32 s67, s52, 0
	s_lshl_b32 s68, s67, 13
	s_mov_b32 s69, 0
	s_mul_i32 s43, s67, 0x1800
	s_add_u32 s70, s54, s43
	s_addc_u32 s71, s55, 0
	s_add_u32 s68, s56, s68
	s_addc_u32 s69, s57, s69
	s_add_i32 s53, s65, 1
	s_cmp_ge_u32 s53, 3
	s_cselect_b32 s42, 3, 0
	s_sub_i32 s53, s53, s42
	s_cmp_eq_u32 s53, 2
	s_cselect_b32 s42, 0x5000, 0
	s_cselect_b32 s43, 0xd000, 0
	s_mul_i32 s67, s53, 0x6000
	s_add_i32 s42, s42, s67
	s_add_i32 s42, s42, 0x8000
	s_add_i32 s42, s58, s42
	s_lshl_b32 s67, s53, 14
	s_add_i32 s43, s43, s67
	s_add_i32 s43, s58, s43
	v_lshl_add_u64 v[64:65], s[70:71], 0, v[156:157]
	v_lshl_add_u64 v[66:67], s[70:71], 0, v[158:159]
	v_lshl_add_u64 v[68:69], s[70:71], 0, v[160:161]
	v_lshl_add_u64 v[70:71], s[68:69], 0, v[162:163]
	v_lshl_add_u64 v[72:73], s[68:69], 0, v[164:165]
	v_lshl_add_u64 v[70:71], v[70:71], 0, s[20:21]
	v_lshl_add_u64 v[72:73], v[72:73], 0, s[20:21]
	s_mov_b32 m0, s42
	s_nop 0
	global_load_lds_dwordx4 v[64:65], off
	s_add_i32 m0, s42, 0x2000
	s_nop 0
	global_load_lds_dwordx4 v[66:67], off
	s_add_i32 m0, s42, 0x4000
	s_nop 0
	global_load_lds_dwordx4 v[68:69], off
	s_mov_b32 m0, s43
	s_nop 0
	global_load_lds_dwordx4 v[70:71], off
	s_add_i32 m0, s43, 0x2000
	s_nop 0
	global_load_lds_dwordx4 v[72:73], off
.Latt_st2:
	s_andn2_b64 vcc, exec, s[50:51]
	s_cbranch_vccz .LBB0_140
	s_add_i32 s42, s66, 2
	s_cmp_ge_i32 s42, s47
	s_cbranch_scc1 .Latt_st_none
	s_add_i32 s67, s52, 64
	s_lshl_b32 s68, s67, 13
	s_mov_b32 s69, 0
	s_mul_i32 s43, s67, 0x1800
	s_add_u32 s70, s54, s43
	s_addc_u32 s71, s55, 0
	s_add_u32 s68, s56, s68
	s_addc_u32 s69, s57, s69
	s_add_i32 s53, s65, 2
	s_cmp_ge_u32 s53, 3
	s_cselect_b32 s42, 3, 0
	s_sub_i32 s53, s53, s42
	s_cmp_eq_u32 s53, 2
	s_cselect_b32 s42, 0x5000, 0
	s_cselect_b32 s43, 0xd000, 0
	s_mul_i32 s67, s53, 0x6000
	s_add_i32 s42, s42, s67
	s_add_i32 s42, s42, 0x8000
	s_add_i32 s42, s58, s42
	s_lshl_b32 s67, s53, 14
	s_add_i32 s43, s43, s67
	s_add_i32 s43, s58, s43
	v_lshl_add_u64 v[64:65], s[70:71], 0, v[156:157]
	v_lshl_add_u64 v[66:67], s[70:71], 0, v[158:159]
	v_lshl_add_u64 v[68:69], s[70:71], 0, v[160:161]
	v_lshl_add_u64 v[70:71], s[68:69], 0, v[162:163]
	v_lshl_add_u64 v[72:73], s[68:69], 0, v[164:165]
	v_lshl_add_u64 v[70:71], v[70:71], 0, s[20:21]
	v_lshl_add_u64 v[72:73], v[72:73], 0, s[20:21]
	s_mov_b32 m0, s42
	s_nop 0
	global_load_lds_dwordx4 v[64:65], off
	s_add_i32 m0, s42, 0x2000
	s_nop 0
	global_load_lds_dwordx4 v[66:67], off
	s_add_i32 m0, s42, 0x4000
	s_nop 0
	global_load_lds_dwordx4 v[68:69], off
	s_mov_b32 m0, s43
	s_nop 0
	global_load_lds_dwordx4 v[70:71], off
	s_add_i32 m0, s43, 0x2000
	s_nop 0
	global_load_lds_dwordx4 v[72:73], off
	s_mov_b32 s71, 1
	s_branch .LBB0_140
.Latt_st_none:
	s_mov_b32 s71, 0
.LBB0_140:
	s_andn2_b64 vcc, exec, s[50:51]
	s_cbranch_vccnz .LBB0_137
	s_mul_i32 s42, s65, 0x6000
	s_cmp_eq_u32 s65, 2
	s_cselect_b32 s43, 0x5000, 0
	s_cselect_b32 s67, 0xd000, 0
	s_add_i32 s42, s42, s43
	s_lshl_b32 s69, s65, 14
	s_add_i32 s69, s69, s67
	v_add_u32_e32 v147, s69, v221
	v_add_u32_e32 v213, s42, v209
	v_add_u32_e32 v214, s42, v210
	ds_read_b128 v[216:219], v213 offset:32768
	ds_read_b128 v[224:227], v214 offset:32768
	ds_read_b128 v[240:243], v213 offset:32896
	ds_read_b128 v[244:247], v214 offset:32896
	v_readfirstlane_b32 s70, v206
	s_nop 3
	s_cmpk_eq_i32 s66, 0x80
	s_cselect_b32 s66, 0x7f800000, s70
	s_add_i32 s67, s52, 64
	s_lshl_b32 s68, s67, 13
	s_mov_b32 s69, 0
	s_mul_i32 s43, s67, 0x1800
	s_add_u32 s70, s54, s43
	s_addc_u32 s71, s55, 0
	s_add_u32 s68, s56, s68
	s_addc_u32 s69, s57, s69
	s_add_i32 s53, s65, 2
	s_cmp_ge_u32 s53, 3
	s_cselect_b32 s42, 3, 0
	s_sub_i32 s53, s53, s42
	s_cmp_eq_u32 s53, 2
	s_cselect_b32 s42, 0x5000, 0
	s_cselect_b32 s43, 0xd000, 0
	s_mul_i32 s67, s53, 0x6000
	s_add_i32 s42, s42, s67
	s_add_i32 s42, s42, 0x8000
	s_add_i32 s42, s58, s42
	s_lshl_b32 s67, s53, 14
	s_add_i32 s43, s43, s67
	s_add_i32 s43, s58, s43
	s_waitcnt lgkmcnt(3)
	v_mfma_f32_16x16x32_bf16 v[64:67], v[216:219], v[96:99], 0
	v_mfma_f32_16x16x32_bf16 v[72:75], v[216:219], v[120:123], 0
	ds_read_b128 v[216:219], v213 offset:33024
	s_waitcnt lgkmcnt(3)
	v_mfma_f32_16x16x32_bf16 v[64:67], v[224:227], v[100:103], v[64:67]
	v_mfma_f32_16x16x32_bf16 v[72:75], v[224:227], v[124:127], v[72:75]
	ds_read_b128 v[224:227], v214 offset:33024
	s_waitcnt lgkmcnt(3)
	v_mfma_f32_16x16x32_bf16 v[64:67], v[240:243], v[104:107], v[64:67]
	v_lshl_add_u64 v[166:167], s[70:71], 0, v[156:157]
	s_mov_b32 m0, s42
	s_nop 0
	global_load_lds_dwordx4 v[166:167], off
	v_mfma_f32_16x16x32_bf16 v[72:75], v[240:243], v[128:131], v[72:75]
	ds_read_b128 v[240:243], v213 offset:38912
	s_waitcnt lgkmcnt(3)
	v_mfma_f32_16x16x32_bf16 v[64:67], v[244:247], v[108:111], v[64:67]
	v_mfma_f32_16x16x32_bf16 v[72:75], v[244:247], v[132:135], v[72:75]
	ds_read_b128 v[244:247], v214 offset:38912
	s_waitcnt lgkmcnt(3)
	v_mfma_f32_16x16x32_bf16 v[64:67], v[216:219], v[112:115], v[64:67]
	v_mfma_f32_16x16x32_bf16 v[72:75], v[216:219], v[136:139], v[72:75]
	ds_read_b128 v[216:219], v213 offset:39040
	s_waitcnt lgkmcnt(3)
	v_mfma_f32_16x16x32_bf16 v[64:67], v[224:227], v[116:119], v[64:67]
	v_mfma_f32_16x16x32_bf16 v[72:75], v[224:227], v[140:143], v[72:75]
	ds_read_b128 v[224:227], v214 offset:39040
	s_waitcnt lgkmcnt(3)
	v_mfma_f32_16x16x32_bf16 v[68:71], v[240:243], v[96:99], 0
	v_mfma_f32_16x16x32_bf16 v[76:79], v[240:243], v[120:123], 0
	ds_read_b128 v[240:243], v213 offset:39168
	s_waitcnt lgkmcnt(3)
	v_mfma_f32_16x16x32_bf16 v[68:71], v[244:247], v[100:103], v[68:71]
	v_mfma_f32_16x16x32_bf16 v[76:79], v[244:247], v[124:127], v[76:79]
	ds_read_b128 v[244:247], v214 offset:39168
	s_waitcnt lgkmcnt(3)
	v_mfma_f32_16x16x32_bf16 v[68:71], v[216:219], v[104:107], v[68:71]
	v_mfma_f32_16x16x32_bf16 v[76:79], v[216:219], v[128:131], v[76:79]
	ds_read_b128 v[216:219], v213 offset:45056
	s_waitcnt lgkmcnt(3)
	v_mfma_f32_16x16x32_bf16 v[68:71], v[224:227], v[108:111], v[68:71]
	v_mfma_f32_16x16x32_bf16 v[76:79], v[224:227], v[132:135], v[76:79]
	ds_read_b128 v[224:227], v214 offset:45056
	s_waitcnt lgkmcnt(3)
	v_mfma_f32_16x16x32_bf16 v[68:71], v[240:243], v[112:115], v[68:71]
	v_lshl_add_u64 v[166:167], s[70:71], 0, v[158:159]
	s_add_i32 m0, s42, 0x2000
	s_nop 0
	global_load_lds_dwordx4 v[166:167], off
	v_mfma_f32_16x16x32_bf16 v[76:79], v[240:243], v[136:139], v[76:79]
	ds_read_b128 v[240:243], v213 offset:45184
	s_waitcnt lgkmcnt(3)
	v_mfma_f32_16x16x32_bf16 v[68:71], v[244:247], v[116:119], v[68:71]
	v_mfma_f32_16x16x32_bf16 v[76:79], v[244:247], v[140:143], v[76:79]
	ds_read_b128 v[244:247], v214 offset:45184
	s_cmp_eq_u32 s66, 0
	s_cbranch_scc1 .Latt_fast
; #define LAS __attribute__((address_space(3)))
; #define SBAR() __builtin_amdgcn_sched_barrier(0)
; __device__ __forceinline__ void qkt(f32x16& p0, f32x16& p1, LAS const unsigned char* Ks, const bf16x8* qr, LAS const unsigned char* qt, int r32, int hi) {
;     p0 = (f32x16){}; p1 = (f32x16){};
; #pragma unroll
;     for (int d0 = 0; d0 < 12; ++d0) { const int cb = (d0 * 16 + hi * 8) * 2;
;         const bf16x8 b0 = *(const LAS bf16x8*)(Ks + KSWZ(r32, cb));
;         const bf16x8 b1 = *(const LAS bf16x8*)(Ks + KSWZ(32 + r32, cb));
;         const bf16x8 qf = d0 < QREG ? qr[d0 < QREG ? d0 : 0] : *(const LAS bf16x8*)(qt + (d0 - QREG) * 1024);
;         p0 = __builtin_amdgcn_mfma_f32_32x32x16_bf16(b0, qf, p0, 0, 0, 0);
;         p1 = __builtin_amdgcn_mfma_f32_32x32x16_bf16(b1, qf, p1, 0, 0, 0);
;         if ((d0 & 3) == 3) SBAR(); }
; }
; __device__ __forceinline__ void expP(f32x16& p0, f32x16& p1, float MB) {
; #pragma unroll
;     for (int r = 0; r < 16; ++r) p0[r] = __builtin_amdgcn_exp2f(p0[r] - MB);
; #pragma unroll
;     for (int r = 0; r < 16; ++r) p1[r] = __builtin_amdgcn_exp2f(p1[r] - MB);
; }
	v_sub_f32_e32 v64, v64, v206
	v_sub_f32_e32 v65, v65, v206
	v_exp_f32_e32 v64, v64
	s_waitcnt lgkmcnt(3)
	v_mfma_f32_16x16x32_bf16 v[80:83], v[216:219], v[96:99], 0
	v_sub_f32_e32 v66, v66, v206
	v_exp_f32_e32 v65, v65
	v_sub_f32_e32 v67, v67, v206
	v_mfma_f32_16x16x32_bf16 v[88:91], v[216:219], v[120:123], 0
	ds_read_b128 v[216:219], v213 offset:45312
	v_exp_f32_e32 v66, v66
	v_subrev_f32_e32 v68, s66, v68
	v_exp_f32_e32 v67, v67
	s_waitcnt lgkmcnt(3)
	v_mfma_f32_16x16x32_bf16 v[80:83], v[224:227], v[100:103], v[80:83]
	v_add_f32_e32 v146, v64, v65
	v_subrev_f32_e32 v69, s66, v69
	v_exp_f32_e32 v68, v68
	v_mfma_f32_16x16x32_bf16 v[88:91], v[224:227], v[124:127], v[88:91]
	ds_read_b128 v[224:227], v214 offset:45312
	v_add_f32_e32 v146, v66, v146
	v_subrev_f32_e32 v70, s66, v70
	v_exp_f32_e32 v69, v69
	s_waitcnt lgkmcnt(3)
	v_mfma_f32_16x16x32_bf16 v[80:83], v[240:243], v[104:107], v[80:83]
	v_add_f32_e32 v146, v67, v146
	v_subrev_f32_e32 v71, s66, v71
	v_exp_f32_e32 v70, v70
	v_mfma_f32_16x16x32_bf16 v[88:91], v[240:243], v[128:131], v[88:91]
	ds_read_b128 v[240:243], v213 offset:51200
	v_add_f32_e32 v146, v68, v146
	v_exp_f32_e32 v71, v71
	s_waitcnt lgkmcnt(3)
	v_mfma_f32_16x16x32_bf16 v[80:83], v[244:247], v[108:111], v[80:83]
	v_add_f32_e32 v146, v69, v146
	v_add_f32_e32 v146, v70, v146
	v_mfma_f32_16x16x32_bf16 v[88:91], v[244:247], v[132:135], v[88:91]
	ds_read_b128 v[244:247], v214 offset:51200
	v_add_f32_e32 v146, v71, v146
	v_cvt_pk_bf16_f32 v64, v64, v65
	s_waitcnt lgkmcnt(3)
	v_mfma_f32_16x16x32_bf16 v[80:83], v[216:219], v[112:115], v[80:83]
	v_cvt_pk_bf16_f32 v65, v66, v67
	v_cvt_pk_bf16_f32 v66, v68, v69
	v_mfma_f32_16x16x32_bf16 v[88:91], v[216:219], v[136:139], v[88:91]
	ds_read_b128 v[216:219], v213 offset:51328
	v_cvt_pk_bf16_f32 v67, v70, v71
	v_sub_f32_e32 v72, v72, v206
	ds_read_b128 v[68:71], v214 offset:51328
	s_waitcnt lgkmcnt(4)
	v_mfma_f32_16x16x32_bf16 v[80:83], v[224:227], v[116:119], v[80:83]
	v_sub_f32_e32 v73, v73, v206
	v_exp_f32_e32 v72, v72
	v_mfma_f32_16x16x32_bf16 v[88:91], v[224:227], v[140:143], v[88:91]
	ds_read_b128 v[224:227], v213 offset:51456
	v_sub_f32_e32 v74, v74, v206
	v_exp_f32_e32 v73, v73
	s_waitcnt lgkmcnt(4)
	v_mfma_f32_16x16x32_bf16 v[84:87], v[240:243], v[96:99], 0
	v_lshl_add_u64 v[166:167], s[70:71], 0, v[160:161]
	s_add_i32 m0, s42, 0x4000
	s_nop 0
	global_load_lds_dwordx4 v[166:167], off
	v_sub_f32_e32 v75, v75, v206
	v_exp_f32_e32 v74, v74
	v_mfma_f32_16x16x32_bf16 v[92:95], v[240:243], v[120:123], 0
	ds_read_b128 v[240:243], v214 offset:51456
	v_subrev_f32_e32 v76, s66, v76
	v_exp_f32_e32 v75, v75
	s_waitcnt lgkmcnt(4)
	v_mfma_f32_16x16x32_bf16 v[84:87], v[244:247], v[100:103], v[84:87]
	v_add_f32_e32 v148, v72, v73
	v_subrev_f32_e32 v77, s66, v77
	v_mfma_f32_16x16x32_bf16 v[92:95], v[244:247], v[124:127], v[92:95]
	ds_read_b64_tr_b16 v[244:245], v147 offset:0
	ds_read_b64_tr_b16 v[246:247], v147 offset:4096
	v_exp_f32_e32 v76, v76
	v_add_f32_e32 v148, v74, v148
	s_waitcnt lgkmcnt(5)
	v_mfma_f32_16x16x32_bf16 v[84:87], v[216:219], v[104:107], v[84:87]
	v_subrev_f32_e32 v78, s66, v78
	v_exp_f32_e32 v77, v77
	v_mfma_f32_16x16x32_bf16 v[92:95], v[216:219], v[128:131], v[92:95]
	ds_read_b64_tr_b16 v[216:217], v147 offset:256
	ds_read_b64_tr_b16 v[218:219], v147 offset:4352
	v_add_f32_e32 v148, v75, v148
	v_subrev_f32_e32 v79, s66, v79
	s_waitcnt lgkmcnt(6)
	v_mfma_f32_16x16x32_bf16 v[84:87], v[68:71], v[108:111], v[84:87]
	v_exp_f32_e32 v78, v78
	v_add_f32_e32 v148, v76, v148
	v_mfma_f32_16x16x32_bf16 v[92:95], v[68:71], v[132:135], v[92:95]
	ds_read_b64_tr_b16 v[68:69], v147 offset:512
	ds_read_b64_tr_b16 v[70:71], v147 offset:4608
	v_exp_f32_e32 v79, v79
	v_add_f32_e32 v148, v77, v148
	s_waitcnt lgkmcnt(7)
	v_mfma_f32_16x16x32_bf16 v[84:87], v[224:227], v[112:115], v[84:87]
	v_add_f32_e32 v148, v78, v148
	v_add_f32_e32 v148, v79, v148
	v_mfma_f32_16x16x32_bf16 v[92:95], v[224:227], v[136:139], v[92:95]
	ds_read_b64_tr_b16 v[224:225], v147 offset:768
	ds_read_b64_tr_b16 v[226:227], v147 offset:4864
	v_cvt_pk_bf16_f32 v72, v72, v73
	v_cvt_pk_bf16_f32 v73, v74, v75
	s_waitcnt lgkmcnt(8)
	v_mfma_f32_16x16x32_bf16 v[84:87], v[240:243], v[116:119], v[84:87]
	v_cvt_pk_bf16_f32 v74, v76, v77
	v_cvt_pk_bf16_f32 v75, v78, v79
	ds_read_b64_tr_b16 v[76:77], v147 offset:1024
	ds_read_b64_tr_b16 v[78:79], v147 offset:5120
	v_mfma_f32_16x16x32_bf16 v[92:95], v[240:243], v[140:143], v[92:95]
	ds_read_b64_tr_b16 v[240:241], v147 offset:1280
	ds_read_b64_tr_b16 v[242:243], v147 offset:5376
	v_subrev_f32_e32 v80, s66, v80
	v_subrev_f32_e32 v81, s66, v81
	v_exp_f32_e32 v80, v80
	v_subrev_f32_e32 v82, s66, v82
	s_waitcnt lgkmcnt(10)
	v_mfma_f32_16x16x32_bf16 v[0:3], v[64:67], v[244:247], v[0:3]
	v_exp_f32_e32 v81, v81
	v_subrev_f32_e32 v83, s66, v83
	v_exp_f32_e32 v82, v82
	v_add_f32_e32 v146, v80, v146
	v_mfma_f32_16x16x32_bf16 v[32:35], v[72:75], v[244:247], v[32:35]
	ds_read_b64_tr_b16 v[244:245], v147 offset:1536
	ds_read_b64_tr_b16 v[246:247], v147 offset:5632
	v_subrev_f32_e32 v84, s66, v84
	v_exp_f32_e32 v83, v83
	v_add_f32_e32 v146, v81, v146
	v_subrev_f32_e32 v85, s66, v85
	s_waitcnt lgkmcnt(10)
	v_mfma_f32_16x16x32_bf16 v[4:7], v[64:67], v[216:219], v[4:7]
	v_exp_f32_e32 v84, v84
	v_add_f32_e32 v146, v82, v146
	v_subrev_f32_e32 v86, s66, v86
	v_exp_f32_e32 v85, v85
	v_mfma_f32_16x16x32_bf16 v[36:39], v[72:75], v[216:219], v[36:39]
	ds_read_b64_tr_b16 v[216:217], v147 offset:1792
	ds_read_b64_tr_b16 v[218:219], v147 offset:5888
	v_add_f32_e32 v146, v83, v146
	v_subrev_f32_e32 v87, s66, v87
	v_exp_f32_e32 v86, v86
	v_add_f32_e32 v146, v84, v146
	s_waitcnt lgkmcnt(10)
; #define SBAR() __builtin_amdgcn_sched_barrier(0)
; __device__ __forceinline__ void pv_d0(f32x16* o, int vb, bf16x8 pa0, bf16x8 pa1, bf16x8 pa2, bf16x8 pa3) {
;     VBlk A, B;
;     pv_load<0>(A, vb); pv_load<1>(B, vb);
;     asm volatile("s_waitcnt lgkmcnt(8)" ::: "memory"); SBAR(); pv_mma(o[0], A, pa0, pa1, pa2, pa3); SBAR();
;     pv_load<2>(A, vb);
;     asm volatile("s_waitcnt lgkmcnt(8)" ::: "memory"); SBAR(); pv_mma(o[1], B, pa0, pa1, pa2, pa3); SBAR();
;     pv_load<3>(B, vb);
;     asm volatile("s_waitcnt lgkmcnt(8)" ::: "memory"); SBAR(); pv_mma(o[2], A, pa0, pa1, pa2, pa3); SBAR();
;     asm volatile("s_waitcnt lgkmcnt(0)" ::: "memory"); SBAR(); pv_mma(o[3], B, pa0, pa1, pa2, pa3); SBAR();
; }
; __device__ __forceinline__ void finishP(const f32x16& p0, const f32x16& p1, float& l_reg, bf16x8& pa0, bf16x8& pa1, bf16x8& pa2, bf16x8& pa3) {
;     float ps = 0.f;
; #pragma unroll
;     for (int r = 0; r < 16; ++r) ps += p0[r];
; #pragma unroll
;     for (int r = 0; r < 16; ++r) ps += p1[r];
;     l_reg += ps;
;     ...
;     PK4(p0, 0, pa0); PK4(p0, 8, pa1); PK4(p1, 0, pa2); PK4(p1, 8, pa3);
;     ...
; }
	v_mfma_f32_16x16x32_bf16 v[8:11], v[64:67], v[68:71], v[8:11]
	v_lshl_add_u64 v[166:167], s[68:69], 0, v[162:163]
	s_mov_b32 m0, s43
	v_lshl_add_u64 v[166:167], v[166:167], 0, s[20:21]
	global_load_lds_dwordx4 v[166:167], off
	v_exp_f32_e32 v87, v87
	v_add_f32_e32 v146, v85, v146
	v_add_f32_e32 v146, v86, v146
	v_add_f32_e32 v146, v87, v146
	v_mfma_f32_16x16x32_bf16 v[40:43], v[72:75], v[68:71], v[40:43]
	ds_read_b64_tr_b16 v[68:69], v147 offset:8192
	ds_read_b64_tr_b16 v[70:71], v147 offset:12288
	v_cvt_pk_bf16_f32 v80, v80, v81
	v_cvt_pk_bf16_f32 v81, v82, v83
	v_cvt_pk_bf16_f32 v82, v84, v85
	v_cvt_pk_bf16_f32 v83, v86, v87
	s_waitcnt lgkmcnt(10)
	v_mfma_f32_16x16x32_bf16 v[12:15], v[64:67], v[224:227], v[12:15]
	v_add_f32_e32 v155, v155, v146
	v_subrev_f32_e32 v88, s66, v88
	v_subrev_f32_e32 v89, s66, v89
	v_exp_f32_e32 v88, v88
	ds_read_b64_tr_b16 v[84:85], v147 offset:8448
	ds_read_b64_tr_b16 v[86:87], v147 offset:12544
	v_mfma_f32_16x16x32_bf16 v[44:47], v[72:75], v[224:227], v[44:47]
	ds_read_b64_tr_b16 v[224:225], v147 offset:8704
	ds_read_b64_tr_b16 v[226:227], v147 offset:12800
	v_subrev_f32_e32 v90, s66, v90
	v_exp_f32_e32 v89, v89
	v_subrev_f32_e32 v91, s66, v91
	v_exp_f32_e32 v90, v90
	s_waitcnt lgkmcnt(12)
	v_mfma_f32_16x16x32_bf16 v[16:19], v[64:67], v[76:79], v[16:19]
	v_add_f32_e32 v148, v88, v148
	v_subrev_f32_e32 v92, s66, v92
	v_exp_f32_e32 v91, v91
	v_add_f32_e32 v148, v89, v148
	v_mfma_f32_16x16x32_bf16 v[48:51], v[72:75], v[76:79], v[48:51]
	ds_read_b64_tr_b16 v[76:77], v147 offset:8960
	ds_read_b64_tr_b16 v[78:79], v147 offset:13056
	v_subrev_f32_e32 v93, s66, v93
	v_exp_f32_e32 v92, v92
	v_add_f32_e32 v148, v90, v148
	s_waitcnt lgkmcnt(12)
	v_mfma_f32_16x16x32_bf16 v[20:23], v[64:67], v[240:243], v[20:23]
	v_subrev_f32_e32 v94, s66, v94
	v_exp_f32_e32 v93, v93
	v_add_f32_e32 v148, v91, v148
	v_mfma_f32_16x16x32_bf16 v[52:55], v[72:75], v[240:243], v[52:55]
	ds_read_b64_tr_b16 v[240:241], v147 offset:9216
	ds_read_b64_tr_b16 v[242:243], v147 offset:13312
	v_subrev_f32_e32 v95, s66, v95
	v_exp_f32_e32 v94, v94
	v_add_f32_e32 v148, v92, v148
	s_waitcnt lgkmcnt(12)
	v_mfma_f32_16x16x32_bf16 v[24:27], v[64:67], v[244:247], v[24:27]
	v_exp_f32_e32 v95, v95
	v_add_f32_e32 v148, v93, v148
	v_add_f32_e32 v148, v94, v148
	v_mfma_f32_16x16x32_bf16 v[56:59], v[72:75], v[244:247], v[56:59]
	ds_read_b64_tr_b16 v[244:245], v147 offset:9472
	ds_read_b64_tr_b16 v[246:247], v147 offset:13568
	v_add_f32_e32 v148, v95, v148
	v_cvt_pk_bf16_f32 v88, v88, v89
	v_cvt_pk_bf16_f32 v89, v90, v91
	s_waitcnt lgkmcnt(12)
	v_mfma_f32_16x16x32_bf16 v[28:31], v[64:67], v[216:219], v[28:31]
	v_cvt_pk_bf16_f32 v90, v92, v93
	v_cvt_pk_bf16_f32 v91, v94, v95
	v_add_f32_e32 v149, v149, v148
	ds_read_b64_tr_b16 v[92:93], v147 offset:9728
	ds_read_b64_tr_b16 v[94:95], v147 offset:13824
	v_mfma_f32_16x16x32_bf16 v[60:63], v[72:75], v[216:219], v[60:63]
	s_waitcnt lgkmcnt(12)
	v_mfma_f32_16x16x32_bf16 v[0:3], v[80:83], v[68:71], v[0:3]
	v_mfma_f32_16x16x32_bf16 v[32:35], v[88:91], v[68:71], v[32:35]
	ds_read_b64_tr_b16 v[216:217], v147 offset:9984
	ds_read_b64_tr_b16 v[218:219], v147 offset:14080
	s_waitcnt lgkmcnt(12)
	v_mfma_f32_16x16x32_bf16 v[4:7], v[80:83], v[84:87], v[4:7]
	v_mfma_f32_16x16x32_bf16 v[36:39], v[88:91], v[84:87], v[36:39]
	s_waitcnt lgkmcnt(10)
	v_mfma_f32_16x16x32_bf16 v[8:11], v[80:83], v[224:227], v[8:11]
	v_lshl_add_u64 v[166:167], s[68:69], 0, v[164:165]
	s_add_i32 m0, s43, 0x2000
	v_lshl_add_u64 v[166:167], v[166:167], 0, s[20:21]
	global_load_lds_dwordx4 v[166:167], off
	v_mfma_f32_16x16x32_bf16 v[40:43], v[88:91], v[224:227], v[40:43]
	s_waitcnt lgkmcnt(8)
	v_mfma_f32_16x16x32_bf16 v[12:15], v[80:83], v[76:79], v[12:15]
	v_mfma_f32_16x16x32_bf16 v[44:47], v[88:91], v[76:79], v[44:47]
	s_waitcnt lgkmcnt(6)
	v_mfma_f32_16x16x32_bf16 v[16:19], v[80:83], v[240:243], v[16:19]
	v_mfma_f32_16x16x32_bf16 v[48:51], v[88:91], v[240:243], v[48:51]
	s_waitcnt lgkmcnt(4)
	v_mfma_f32_16x16x32_bf16 v[20:23], v[80:83], v[244:247], v[20:23]
	v_mfma_f32_16x16x32_bf16 v[52:55], v[88:91], v[244:247], v[52:55]
	s_waitcnt lgkmcnt(2)
	v_mfma_f32_16x16x32_bf16 v[24:27], v[80:83], v[92:95], v[24:27]
	v_mfma_f32_16x16x32_bf16 v[56:59], v[88:91], v[92:95], v[56:59]
	s_waitcnt lgkmcnt(0)
	v_mfma_f32_16x16x32_bf16 v[28:31], v[80:83], v[216:219], v[28:31]
	v_mfma_f32_16x16x32_bf16 v[60:63], v[88:91], v[216:219], v[60:63]
	s_mov_b32 s71, 1
	s_branch .LBB0_137
; #define LAS __attribute__((address_space(3)))
; #define SBAR() __builtin_amdgcn_sched_barrier(0)
; __device__ __forceinline__ void qkt(f32x16& p0, f32x16& p1, LAS const unsigned char* Ks, const bf16x8* qr, LAS const unsigned char* qt, int r32, int hi) {
;     p0 = (f32x16){}; p1 = (f32x16){};
; #pragma unroll
;     for (int d0 = 0; d0 < 12; ++d0) { const int cb = (d0 * 16 + hi * 8) * 2;
;         const bf16x8 b0 = *(const LAS bf16x8*)(Ks + KSWZ(r32, cb));
;         const bf16x8 b1 = *(const LAS bf16x8*)(Ks + KSWZ(32 + r32, cb));
;         const bf16x8 qf = d0 < QREG ? qr[d0 < QREG ? d0 : 0] : *(const LAS bf16x8*)(qt + (d0 - QREG) * 1024);
;         p0 = __builtin_amdgcn_mfma_f32_32x32x16_bf16(b0, qf, p0, 0, 0, 0);
;         p1 = __builtin_amdgcn_mfma_f32_32x32x16_bf16(b1, qf, p1, 0, 0, 0);
;         if ((d0 & 3) == 3) SBAR(); }
; }
; __device__ __forceinline__ void expP(f32x16& p0, f32x16& p1, float MB) {
; #pragma unroll
;     for (int r = 0; r < 16; ++r) p0[r] = __builtin_amdgcn_exp2f(p0[r] - MB);
; #pragma unroll
;     for (int r = 0; r < 16; ++r) p1[r] = __builtin_amdgcn_exp2f(p1[r] - MB);
; }
.Latt_fast:
	v_exp_f32_e32 v64, v64
	v_exp_f32_e32 v65, v65
	s_waitcnt lgkmcnt(3)
	v_mfma_f32_16x16x32_bf16 v[80:83], v[216:219], v[96:99], 0
	v_exp_f32_e32 v66, v66
	v_exp_f32_e32 v67, v67
	v_mfma_f32_16x16x32_bf16 v[88:91], v[216:219], v[120:123], 0
	ds_read_b128 v[216:219], v213 offset:45312
	v_add_f32_e32 v146, v64, v65
	v_exp_f32_e32 v68, v68
	s_waitcnt lgkmcnt(3)
	v_mfma_f32_16x16x32_bf16 v[80:83], v[224:227], v[100:103], v[80:83]
	v_add_f32_e32 v146, v66, v146
	v_exp_f32_e32 v69, v69
	v_mfma_f32_16x16x32_bf16 v[88:91], v[224:227], v[124:127], v[88:91]
	ds_read_b128 v[224:227], v214 offset:45312
	v_add_f32_e32 v146, v67, v146
	v_exp_f32_e32 v70, v70
	s_waitcnt lgkmcnt(3)
	v_mfma_f32_16x16x32_bf16 v[80:83], v[240:243], v[104:107], v[80:83]
	v_add_f32_e32 v146, v68, v146
	v_exp_f32_e32 v71, v71
	v_mfma_f32_16x16x32_bf16 v[88:91], v[240:243], v[128:131], v[88:91]
	ds_read_b128 v[240:243], v213 offset:51200
	v_add_f32_e32 v146, v69, v146
	v_add_f32_e32 v146, v70, v146
	s_waitcnt lgkmcnt(3)
	v_mfma_f32_16x16x32_bf16 v[80:83], v[244:247], v[108:111], v[80:83]
	v_add_f32_e32 v146, v71, v146
	v_cvt_pk_bf16_f32 v64, v64, v65
	v_mfma_f32_16x16x32_bf16 v[88:91], v[244:247], v[132:135], v[88:91]
	ds_read_b128 v[244:247], v214 offset:51200
	v_cvt_pk_bf16_f32 v65, v66, v67
	v_cvt_pk_bf16_f32 v66, v68, v69
	s_waitcnt lgkmcnt(3)
	v_mfma_f32_16x16x32_bf16 v[80:83], v[216:219], v[112:115], v[80:83]
	v_cvt_pk_bf16_f32 v67, v70, v71
	v_exp_f32_e32 v72, v72
	ds_read_b128 v[68:71], v213 offset:51328
	v_mfma_f32_16x16x32_bf16 v[88:91], v[216:219], v[136:139], v[88:91]
	ds_read_b128 v[216:219], v214 offset:51328
	v_exp_f32_e32 v73, v73
	v_exp_f32_e32 v74, v74
	s_waitcnt lgkmcnt(4)
	v_mfma_f32_16x16x32_bf16 v[80:83], v[224:227], v[116:119], v[80:83]
	v_exp_f32_e32 v75, v75
	v_add_f32_e32 v148, v72, v73
	v_mfma_f32_16x16x32_bf16 v[88:91], v[224:227], v[140:143], v[88:91]
	ds_read_b128 v[224:227], v213 offset:51456
	v_exp_f32_e32 v76, v76
	v_add_f32_e32 v148, v74, v148
	s_waitcnt lgkmcnt(4)
	v_mfma_f32_16x16x32_bf16 v[84:87], v[240:243], v[96:99], 0
	v_lshl_add_u64 v[166:167], s[70:71], 0, v[160:161]
	s_add_i32 m0, s42, 0x4000
	s_nop 0
	global_load_lds_dwordx4 v[166:167], off
	v_exp_f32_e32 v77, v77
	v_add_f32_e32 v148, v75, v148
	v_mfma_f32_16x16x32_bf16 v[92:95], v[240:243], v[120:123], 0
	ds_read_b128 v[240:243], v214 offset:51456
	v_exp_f32_e32 v78, v78
	s_waitcnt lgkmcnt(4)
	v_mfma_f32_16x16x32_bf16 v[84:87], v[244:247], v[100:103], v[84:87]
	v_add_f32_e32 v148, v76, v148
	v_mfma_f32_16x16x32_bf16 v[92:95], v[244:247], v[124:127], v[92:95]
	ds_read_b64_tr_b16 v[244:245], v147 offset:0
	ds_read_b64_tr_b16 v[246:247], v147 offset:4096
	v_exp_f32_e32 v79, v79
	s_waitcnt lgkmcnt(5)
	v_mfma_f32_16x16x32_bf16 v[84:87], v[68:71], v[104:107], v[84:87]
	v_add_f32_e32 v148, v77, v148
	v_mfma_f32_16x16x32_bf16 v[92:95], v[68:71], v[128:131], v[92:95]
	ds_read_b64_tr_b16 v[68:69], v147 offset:256
	ds_read_b64_tr_b16 v[70:71], v147 offset:4352
	v_add_f32_e32 v148, v78, v148
	s_waitcnt lgkmcnt(6)
	v_mfma_f32_16x16x32_bf16 v[84:87], v[216:219], v[108:111], v[84:87]
	v_add_f32_e32 v148, v79, v148
	v_mfma_f32_16x16x32_bf16 v[92:95], v[216:219], v[132:135], v[92:95]
	ds_read_b64_tr_b16 v[216:217], v147 offset:512
	ds_read_b64_tr_b16 v[218:219], v147 offset:4608
	v_cvt_pk_bf16_f32 v72, v72, v73
	s_waitcnt lgkmcnt(7)
	v_mfma_f32_16x16x32_bf16 v[84:87], v[224:227], v[112:115], v[84:87]
	v_cvt_pk_bf16_f32 v73, v74, v75
	v_mfma_f32_16x16x32_bf16 v[92:95], v[224:227], v[136:139], v[92:95]
	ds_read_b64_tr_b16 v[224:225], v147 offset:768
	ds_read_b64_tr_b16 v[226:227], v147 offset:4864
	v_cvt_pk_bf16_f32 v74, v76, v77
	s_waitcnt lgkmcnt(8)
	v_mfma_f32_16x16x32_bf16 v[84:87], v[240:243], v[116:119], v[84:87]
	v_cvt_pk_bf16_f32 v75, v78, v79
	ds_read_b64_tr_b16 v[76:77], v147 offset:1024
	ds_read_b64_tr_b16 v[78:79], v147 offset:5120
	v_mfma_f32_16x16x32_bf16 v[92:95], v[240:243], v[140:143], v[92:95]
	ds_read_b64_tr_b16 v[240:241], v147 offset:1280
	ds_read_b64_tr_b16 v[242:243], v147 offset:5376
	v_exp_f32_e32 v80, v80
	v_exp_f32_e32 v81, v81
	v_exp_f32_e32 v82, v82
	s_waitcnt lgkmcnt(10)
	v_mfma_f32_16x16x32_bf16 v[0:3], v[64:67], v[244:247], v[0:3]
	v_add_f32_e32 v146, v80, v146
	v_exp_f32_e32 v83, v83
	v_add_f32_e32 v146, v81, v146
	v_mfma_f32_16x16x32_bf16 v[32:35], v[72:75], v[244:247], v[32:35]
	ds_read_b64_tr_b16 v[244:245], v147 offset:1536
	ds_read_b64_tr_b16 v[246:247], v147 offset:5632
	v_exp_f32_e32 v84, v84
	v_add_f32_e32 v146, v82, v146
	v_exp_f32_e32 v85, v85
	s_waitcnt lgkmcnt(10)
; #define SBAR() __builtin_amdgcn_sched_barrier(0)
; __device__ __forceinline__ void pv_d0(f32x16* o, int vb, bf16x8 pa0, bf16x8 pa1, bf16x8 pa2, bf16x8 pa3) {
;     VBlk A, B;
;     pv_load<0>(A, vb); pv_load<1>(B, vb);
;     asm volatile("s_waitcnt lgkmcnt(8)" ::: "memory"); SBAR(); pv_mma(o[0], A, pa0, pa1, pa2, pa3); SBAR();
;     pv_load<2>(A, vb);
;     asm volatile("s_waitcnt lgkmcnt(8)" ::: "memory"); SBAR(); pv_mma(o[1], B, pa0, pa1, pa2, pa3); SBAR();
;     pv_load<3>(B, vb);
;     asm volatile("s_waitcnt lgkmcnt(8)" ::: "memory"); SBAR(); pv_mma(o[2], A, pa0, pa1, pa2, pa3); SBAR();
;     asm volatile("s_waitcnt lgkmcnt(0)" ::: "memory"); SBAR(); pv_mma(o[3], B, pa0, pa1, pa2, pa3); SBAR();
; }
	v_mfma_f32_16x16x32_bf16 v[4:7], v[64:67], v[68:71], v[4:7]
	v_add_f32_e32 v146, v83, v146
	v_exp_f32_e32 v86, v86
	v_add_f32_e32 v146, v84, v146
	v_mfma_f32_16x16x32_bf16 v[36:39], v[72:75], v[68:71], v[36:39]
	ds_read_b64_tr_b16 v[68:69], v147 offset:1792
	ds_read_b64_tr_b16 v[70:71], v147 offset:5888
	v_exp_f32_e32 v87, v87
	v_add_f32_e32 v146, v85, v146
	v_add_f32_e32 v146, v86, v146
	s_waitcnt lgkmcnt(10)
	v_mfma_f32_16x16x32_bf16 v[8:11], v[64:67], v[216:219], v[8:11]
	v_lshl_add_u64 v[166:167], s[68:69], 0, v[162:163]
	s_mov_b32 m0, s43
	v_lshl_add_u64 v[166:167], v[166:167], 0, s[20:21]
	global_load_lds_dwordx4 v[166:167], off
	v_add_f32_e32 v146, v87, v146
	v_cvt_pk_bf16_f32 v80, v80, v81
	v_cvt_pk_bf16_f32 v81, v82, v83
	v_mfma_f32_16x16x32_bf16 v[40:43], v[72:75], v[216:219], v[40:43]
	ds_read_b64_tr_b16 v[216:217], v147 offset:8192
	ds_read_b64_tr_b16 v[218:219], v147 offset:12288
	v_cvt_pk_bf16_f32 v82, v84, v85
	v_cvt_pk_bf16_f32 v83, v86, v87
	v_add_f32_e32 v155, v155, v146
	ds_read_b64_tr_b16 v[84:85], v147 offset:8448
	ds_read_b64_tr_b16 v[86:87], v147 offset:12544
	s_waitcnt lgkmcnt(12)
	v_mfma_f32_16x16x32_bf16 v[12:15], v[64:67], v[224:227], v[12:15]
	v_exp_f32_e32 v88, v88
	v_exp_f32_e32 v89, v89
	v_exp_f32_e32 v90, v90
	v_mfma_f32_16x16x32_bf16 v[44:47], v[72:75], v[224:227], v[44:47]
	ds_read_b64_tr_b16 v[224:225], v147 offset:8704
	ds_read_b64_tr_b16 v[226:227], v147 offset:12800
	v_add_f32_e32 v148, v88, v148
	v_exp_f32_e32 v91, v91
	v_add_f32_e32 v148, v89, v148
	s_waitcnt lgkmcnt(12)
	v_mfma_f32_16x16x32_bf16 v[16:19], v[64:67], v[76:79], v[16:19]
	v_exp_f32_e32 v92, v92
	v_add_f32_e32 v148, v90, v148
	v_exp_f32_e32 v93, v93
	v_mfma_f32_16x16x32_bf16 v[48:51], v[72:75], v[76:79], v[48:51]
	ds_read_b64_tr_b16 v[76:77], v147 offset:8960
	ds_read_b64_tr_b16 v[78:79], v147 offset:13056
	v_add_f32_e32 v148, v91, v148
	v_exp_f32_e32 v94, v94
	s_waitcnt lgkmcnt(12)
	v_mfma_f32_16x16x32_bf16 v[20:23], v[64:67], v[240:243], v[20:23]
	v_add_f32_e32 v148, v92, v148
	v_exp_f32_e32 v95, v95
	v_mfma_f32_16x16x32_bf16 v[52:55], v[72:75], v[240:243], v[52:55]
	ds_read_b64_tr_b16 v[240:241], v147 offset:9216
	ds_read_b64_tr_b16 v[242:243], v147 offset:13312
	v_add_f32_e32 v148, v93, v148
	v_add_f32_e32 v148, v94, v148
	s_waitcnt lgkmcnt(12)
	v_mfma_f32_16x16x32_bf16 v[24:27], v[64:67], v[244:247], v[24:27]
	v_add_f32_e32 v148, v95, v148
	v_cvt_pk_bf16_f32 v88, v88, v89
	v_mfma_f32_16x16x32_bf16 v[56:59], v[72:75], v[244:247], v[56:59]
	ds_read_b64_tr_b16 v[244:245], v147 offset:9472
	ds_read_b64_tr_b16 v[246:247], v147 offset:13568
	v_cvt_pk_bf16_f32 v89, v90, v91
	v_cvt_pk_bf16_f32 v90, v92, v93
	s_waitcnt lgkmcnt(12)
	v_mfma_f32_16x16x32_bf16 v[28:31], v[64:67], v[68:71], v[28:31]
	v_cvt_pk_bf16_f32 v91, v94, v95
	v_add_f32_e32 v149, v149, v148
	ds_read_b64_tr_b16 v[92:93], v147 offset:9728
	ds_read_b64_tr_b16 v[94:95], v147 offset:13824
	v_mfma_f32_16x16x32_bf16 v[60:63], v[72:75], v[68:71], v[60:63]
	s_waitcnt lgkmcnt(12)
	v_mfma_f32_16x16x32_bf16 v[0:3], v[80:83], v[216:219], v[0:3]
	v_mfma_f32_16x16x32_bf16 v[32:35], v[88:91], v[216:219], v[32:35]
	ds_read_b64_tr_b16 v[68:69], v147 offset:9984
	ds_read_b64_tr_b16 v[70:71], v147 offset:14080
	s_waitcnt lgkmcnt(12)
	v_mfma_f32_16x16x32_bf16 v[4:7], v[80:83], v[84:87], v[4:7]
	v_mfma_f32_16x16x32_bf16 v[36:39], v[88:91], v[84:87], v[36:39]
	s_waitcnt lgkmcnt(10)
	v_mfma_f32_16x16x32_bf16 v[8:11], v[80:83], v[224:227], v[8:11]
	v_lshl_add_u64 v[166:167], s[68:69], 0, v[164:165]
	s_add_i32 m0, s43, 0x2000
	v_lshl_add_u64 v[166:167], v[166:167], 0, s[20:21]
	global_load_lds_dwordx4 v[166:167], off
	v_mfma_f32_16x16x32_bf16 v[40:43], v[88:91], v[224:227], v[40:43]
	s_waitcnt lgkmcnt(8)
	v_mfma_f32_16x16x32_bf16 v[12:15], v[80:83], v[76:79], v[12:15]
	v_mfma_f32_16x16x32_bf16 v[44:47], v[88:91], v[76:79], v[44:47]
	s_waitcnt lgkmcnt(6)
	v_mfma_f32_16x16x32_bf16 v[16:19], v[80:83], v[240:243], v[16:19]
	v_mfma_f32_16x16x32_bf16 v[48:51], v[88:91], v[240:243], v[48:51]
	s_waitcnt lgkmcnt(4)
	v_mfma_f32_16x16x32_bf16 v[20:23], v[80:83], v[244:247], v[20:23]
	v_mfma_f32_16x16x32_bf16 v[52:55], v[88:91], v[244:247], v[52:55]
	s_waitcnt lgkmcnt(2)
	v_mfma_f32_16x16x32_bf16 v[24:27], v[80:83], v[92:95], v[24:27]
	v_mfma_f32_16x16x32_bf16 v[56:59], v[88:91], v[92:95], v[56:59]
	s_waitcnt lgkmcnt(0)
	v_mfma_f32_16x16x32_bf16 v[28:31], v[80:83], v[68:71], v[28:31]
	v_mfma_f32_16x16x32_bf16 v[60:63], v[88:91], v[68:71], v[60:63]
	s_mov_b32 s71, 1
	s_branch .LBB0_137
.LBB0_142:
	s_waitcnt vmcnt(0)
	v_readlane_b32 s64, v254, 44
	v_readlane_b32 s65, v254, 45
	s_and_b64 s[46:47], s[8:9], s[50:51]
	s_andn2_b64 vcc, exec, s[46:47]
	s_mov_b64 s[52:53], -1
	s_cbranch_vccz .LBB0_135
